# ping-pong v7 + next unit's Q / mask / first two K,V tiles issued under the current unit's epilogue
# speedup vs baseline: 1.0059x; 1.0059x over previous
.Lpp_post:
	s_nop 2
	v_rcp_f32_e32 v3, v50
	v_rcp_f32_e32 v4, v51
	s_waitcnt vmcnt(0)
	s_cmp_eq_u32 s26, 3
	s_cbranch_scc1 .Lat_nopf
	s_cmp_eq_u32 s26, 0
	s_cselect_b32 s36, s17, s18
	s_cmp_eq_u32 s26, 2
	s_cselect_b32 s36, s19, s36
	s_lshl_b32 s36, s36, 8
	s_add_i32 s36, s36, s16
	s_add_u32 s6, s8, s36
	s_addc_u32 s7, s9, 0
	s_lshl_b64 s[6:7], s[6:7], 10
	v_lshl_add_u64 v[150:151], v[114:115], 0, s[6:7]
	s_mov_b32 s6, s36
	s_mov_b32 s7, 0
	v_lshl_add_u64 v[136:137], s[6:7], 3, v[120:121]
	s_waitcnt lgkmcnt(0)
	s_barrier
	global_load_dwordx4 v[98:101], v[150:151], off offset:32
	global_load_dwordx4 v[102:105], v[150:151], off offset:64
	global_load_dwordx4 v[106:109], v[150:151], off offset:96
	global_load_dwordx4 v[110:113], v[150:151], off
	global_load_dwordx2 v[138:139], v[136:137], off
	s_mov_b32 m0, s21
	s_nop 0
	global_load_lds_dwordx4 v[116:117], off
	s_mov_b32 m0, s22
	s_nop 0
	global_load_lds_dwordx4 v[118:119], off
	s_mov_b32 m0, s23
	s_nop 0
	global_load_lds_dwordx4 v[122:123], off
	s_mov_b32 m0, s24
	s_nop 0
	global_load_lds_dwordx4 v[124:125], off

.LBB0_952:
	s_lshl_b32 s6, s5, 8
	s_add_i32 s14, s6, s16
	s_add_u32 s12, s8, s14
	s_addc_u32 s13, s9, 0
	s_lshl_b64 s[6:7], s[12:13], 10
	v_lshl_add_u64 v[4:5], v[114:115], 0, s[6:7]
	s_mov_b32 s15, s11
	v_mov_b32_e32 v16, v2
	s_cmp_lg_u32 s26, 0
	s_cbranch_scc1 .Lat_skip
	global_load_dwordx4 v[98:101], v[4:5], off offset:32
	global_load_dwordx4 v[102:105], v[4:5], off offset:64
	global_load_dwordx4 v[106:109], v[4:5], off offset:96
	v_lshl_add_u64 v[136:137], s[14:15], 3, v[120:121]
	global_load_dwordx4 v[110:113], v[4:5], off
	global_load_dwordx2 v[138:139], v[136:137], off
	s_waitcnt lgkmcnt(0)
	s_barrier
	s_mov_b32 m0, s21
	global_load_lds_dwordx4 v[116:117], off
	s_mov_b32 m0, s22
	global_load_lds_dwordx4 v[118:119], off
	v_mov_b32_e32 v16, v2
	s_mov_b32 m0, s23
	global_load_lds_dwordx4 v[122:123], off
	s_mov_b32 m0, s24
	global_load_lds_dwordx4 v[124:125], off
.Lat_skip:
	s_waitcnt vmcnt(2)
	v_mov_b32_e32 v17, v2
	s_lshl_b32 s6, s5, 2
	s_lshl_b32 s30, s5, 10
	v_mov_b32_e32 v3, v2
	v_mov_b32_e32 v4, v2
	v_mov_b32_e32 v5, v2
	v_mov_b32_e32 v6, v2
	v_mov_b32_e32 v7, v2
	v_mov_b32_e32 v8, v2
	v_mov_b32_e32 v9, v2
	v_mov_b32_e32 v10, v2
	v_mov_b32_e32 v11, v2
	v_mov_b32_e32 v12, v2
	v_mov_b32_e32 v13, v2
	v_mov_b32_e32 v14, v2
	v_mov_b32_e32 v15, v2
	v_mov_b64_e32 v[48:49], v[16:17]
	v_mov_b64_e32 v[32:33], v[16:17]
	v_mov_b64_e32 v[64:65], v[16:17]
	s_mov_b32 s15, 2
	s_add_i32 s27, s6, 4
	s_lshr_b32 s28, s14, 6
	s_or_b32 s29, s6, 3
	v_add_u32_e32 v148, s30, v142
	s_addk_i32 s30, 0x400
	s_mov_b32 s31, 0
	s_movk_i32 s33, 0xaf
	v_mov_b64_e32 v[46:47], v[14:15]
	v_mov_b64_e32 v[44:45], v[12:13]
	v_mov_b64_e32 v[42:43], v[10:11]
	v_mov_b64_e32 v[40:41], v[8:9]
	v_mov_b64_e32 v[38:39], v[6:7]
	v_mov_b64_e32 v[36:37], v[4:5]
	v_mov_b64_e32 v[34:35], v[2:3]
	v_mov_b64_e32 v[30:31], v[14:15]
	v_mov_b64_e32 v[28:29], v[12:13]
	v_mov_b64_e32 v[26:27], v[10:11]
	v_mov_b64_e32 v[24:25], v[8:9]
	v_mov_b64_e32 v[22:23], v[6:7]
	v_mov_b64_e32 v[20:21], v[4:5]
	v_mov_b64_e32 v[18:19], v[2:3]
	v_mov_b64_e32 v[62:63], v[14:15]
	v_mov_b64_e32 v[60:61], v[12:13]
	v_mov_b64_e32 v[58:59], v[10:11]
	v_mov_b64_e32 v[56:57], v[8:9]
	v_mov_b64_e32 v[54:55], v[6:7]
	v_mov_b64_e32 v[52:53], v[4:5]
	v_mov_b64_e32 v[50:51], v[2:3]
	s_mov_b32 s34, 0
	s_cmp_lt_u32 s93, 4
	s_cbranch_scc1 .Lpp_pre
	s_barrier
